# G1 last round (64 tiles) split into (ai,bj) quarter tiles over all 256 CUs; mode test placed before the phase barrier
# baseline (speedup 1.0000x reference)
; #define LAS __attribute__((address_space(3)))
; __device__ __forceinline__ unsigned xb_add(unsigned* p, unsigned v) { return __hip_atomic_fetch_add(p, v, __ATOMIC_RELAXED, __HIP_MEMORY_SCOPE_AGENT); }
; __device__ __forceinline__ unsigned xb_xcc_id() { return (unsigned)__builtin_amdgcn_s_getreg((3 << 11) | 20) & 0xFu; }
; __device__ __forceinline__ XcdBarrier xcd_barrier_post(unsigned* bar, volatile LAS unsigned* st) {
;     XcdBarrier b; b.bar = bar; b.x = xb_xcc_id(); b.st = st;
;     if (threadIdx.x == 0) (void)xb_add(&bar[XB_XCNT(b.x)], 1u);
;     return b;
; }
; __global__ void __launch_bounds__(NTHR, 2) mega_fwd(Args args) {
;     extern __shared__ __attribute__((aligned(16))) unsigned char lds_raw[];
;     LAS unsigned char* lds = (LAS unsigned char*)lds_raw;
;     cg::grid_group grid = cg::this_grid();
;     volatile LAS unsigned* bst = (volatile LAS unsigned*)(lds + LDS_BYTES - 64);
;     if (threadIdx.x < 16) bst[threadIdx.x] = 0u;
;     __syncthreads();
;     XcdBarrier xbar = xcd_barrier_post((unsigned*)(args.ws + WS_BAR), bst);
_Z8mega_fwd4Args:
	s_load_dwordx8 s[24:31], s[0:1], 0xa0
	s_mov_b32 s100, 15
	s_mov_b32 s101, 15
	s_load_dwordx8 s[4:11], s[0:1], 0x80
	s_load_dwordx2 s[90:91], s[0:1], 0xc0
	s_mov_b32 s89, s2
	s_add_u32 s2, s0, 0xc0
	s_addc_u32 s3, s1, 0
	s_waitcnt lgkmcnt(0)
	v_writelane_b32 v251, s4, 0
	v_and_b32_e32 v141, 0x3ff, v0
	v_cmp_gt_u32_e32 vcc, 16, v141
	v_writelane_b32 v251, s5, 1
	v_writelane_b32 v251, s6, 2
	v_writelane_b32 v251, s7, 3
	v_writelane_b32 v251, s8, 4
	v_writelane_b32 v251, s9, 5
	v_writelane_b32 v251, s10, 6
	v_writelane_b32 v251, s11, 7
	v_writelane_b32 v251, s2, 8
	s_nop 1
	v_writelane_b32 v251, s3, 9
	s_and_saveexec_b64 s[2:3], vcc
	v_lshl_add_u32 v1, v141, 2, 0
	v_add_u32_e32 v1, 0x23fc0, v1
	v_mov_b32_e32 v2, 0
	ds_write_b32 v1, v2
	s_or_b64 exec, exec, s[2:3]
	s_waitcnt lgkmcnt(0)
	s_barrier
	s_add_u32 s2, s28, 0xc00000
	s_getreg_b32 s4, hwreg(HW_REG_XCC_ID, 0, 4)
	s_addc_u32 s3, s29, 0
	s_and_b32 s6, s4, 15
	v_cmp_eq_u32_e64 s[68:69], 0, v141
	s_and_saveexec_b64 s[4:5], s[68:69]
	s_cbranch_execz .LBB0_5
	s_mov_b64 s[8:9], exec
	v_mbcnt_lo_u32_b32 v1, s8, 0
	v_mbcnt_hi_u32_b32 v1, s9, v1
	v_cmp_eq_u32_e32 vcc, 0, v1
	s_and_b64 s[10:11], exec, vcc
	s_mov_b64 exec, s[10:11]
	s_cbranch_execz .LBB0_5
	s_lshl_b32 s7, s6, 8
	s_bcnt1_i32_b64 s8, s[8:9]
	v_mov_b32_e32 v1, s7
	v_mov_b32_e32 v2, s8
	global_atomic_add v1, v2, s[2:3] offset:1024

;     __host__ __device__ bool next(int i, Unit& u) const {
;         const long L = (long)i * G + c; if (L >= nwg) return false;
;         int wgid = (int)L; { const int q = nwg / NXCD, r = nwg % NXCD, xcd = wgid % NXCD, off = wgid / NXCD; wgid = (xcd < r ? xcd * (q + 1) : r * (q + 1) + (xcd - r) * q) + off; }
;         const int nig = WGM * nN, gid = wgid / nig, fm = gid * WGM, gsz = (nM - fm) < WGM ? (nM - fm) : WGM;
;         u.pm = fm + ((wgid % nig) % gsz); u.pn = (wgid % nig) / gsz; return true;
; template <class Epi, class Sched, bool ALIGN_EPI = false, bool SP2 = false>
; __device__ __forceinline__ void gemm_phase(PG8_LAS unsigned char* lds, const Gemm g, const Sched& S, const Epi& E) {
;     ...
;         const bool has_next = S.next(ui + 1, nxt);
.LBB0_415:
	s_add_i32 s69, s69, 1
	v_readlane_b32 s2, v251, 26
	s_mul_i32 s2, s69, s2
	s_mul_hi_u32 s3, s69, s90
	s_add_i32 s3, s3, s2
	s_mul_i32 s2, s69, s90
	s_mov_b32 s100, s101
	s_lshr_b32 s101, s89, 6
	s_lshl_b32 s101, 1, s101
	s_and_b32 s38, s89, 63
	s_cmp_eq_u32 s69, 12
	s_cselect_b32 vcc_lo, 1, 0
	s_cmpk_eq_i32 s90, 0x100
	s_cselect_b32 vcc_hi, 1, 0
	s_and_b32 vcc_lo, vcc_lo, vcc_hi
	s_cmp_lg_u32 vcc_lo, 0
	s_cselect_b32 s101, s101, 15
	s_cselect_b32 s38, s38, s89
	s_add_u32 s2, s2, s38
	v_readlane_b32 s38, v251, 25
	s_addc_u32 s3, s3, s38
	v_cmp_gt_i64_e32 vcc, s[2:3], v[148:149]
	v_cmp_lt_i64_e64 s[38:39], s[2:3], v[146:147]
	s_cbranch_vccnz .LBB0_417
	s_ashr_i32 s3, s2, 31
	s_lshr_b32 s3, s3, 29
	s_add_i32 s3, s2, s3
	s_ashr_i32 s48, s3, 3
	s_and_b32 s3, s3, -8
	s_sub_i32 s2, s2, s3
	s_cmp_lt_i32 s2, 0
	s_movk_i32 s3, 0x189
	s_cselect_b32 s3, s3, 0x188
	s_mul_i32 s2, s2, s3
	s_add_i32 s2, s2, s48
	s_mul_hi_i32 s3, s2, 0x5397829d
	s_lshr_b32 s48, s3, 31
	s_ashr_i32 s3, s3, 7
	s_add_i32 s3, s3, s48
	s_lshl_b32 s49, s3, 3
	s_sub_i32 s48, 64, s49
	s_min_i32 s50, s48, 8
	s_abs_i32 s48, s50
	v_cvt_f32_u32_e32 v2, s48
	s_sub_i32 s52, 0, s48
	s_mulk_i32 s3, 0x188
	s_sub_i32 s2, s2, s3
	v_rcp_iflag_f32_e32 v2, v2
	s_abs_i32 s3, s2
	s_xor_b32 s51, s2, s50
	s_ashr_i32 s51, s51, 31
	v_mul_f32_e32 v2, 0x4f7ffffe, v2
	v_cvt_u32_f32_e32 v2, v2
	s_nop 0
	v_readfirstlane_b32 s53, v2
	s_mul_i32 s52, s52, s53
	s_mul_hi_u32 s52, s53, s52
	s_add_i32 s53, s53, s52
	s_mul_hi_u32 s52, s3, s53
	s_mul_i32 s53, s52, s48
	s_sub_i32 s3, s3, s53
	s_add_i32 s54, s52, 1
	s_sub_i32 s53, s3, s48
	s_cmp_ge_u32 s3, s48
	s_cselect_b32 s52, s54, s52
	s_cselect_b32 s3, s53, s3
	s_add_i32 s53, s52, 1
	s_cmp_ge_u32 s3, s48
	s_cselect_b32 s3, s53, s52
	s_xor_b32 s3, s3, s51
	s_sub_i32 s48, s3, s51
	s_mul_i32 s3, s48, s50
	s_sub_i32 s2, s2, s3
	s_add_i32 s50, s49, s2

; #define PG8_STAGE(bufoff, gbase, voff) do { _Pragma("unroll") for (int _i = 0; _i < 2; ++_i) \
;         __builtin_amdgcn_global_load_lds((const unsigned*)((const char*)(gbase) + (voff)[_i]), (PG8_LAS unsigned*)(lds + (bufoff) + ldsw + _i * 8192), 16, 0, 0); } while (0)
; #define PG8_LDA(dst, b, h) do { _Pragma("unroll") for (int m = 0; m < 4; ++m) _Pragma("unroll") for (int k = 0; k < 2; ++k) dst[m][k] = *(const PG8_LAS bf16x8*)(lds + PG8_SA(b, h) + aoff + m * 2048 + k * 1024); } while (0)
; #define PG8_LDB(dst, b, h) do { _Pragma("unroll") for (int n = 0; n < 2; ++n) _Pragma("unroll") for (int k = 0; k < 2; ++k) dst[n][k] = *(const PG8_LAS bf16x8*)(lds + PG8_SB(b, h) + boff + n * 2048 + k * 1024); } while (0)
; #define PG8_MMA(ai, bj, At, Bt) do { __builtin_amdgcn_s_setprio(1); _Pragma("unroll") for (int m = 0; m < 4; ++m) _Pragma("unroll") for (int n = 0; n < 2; ++n) _Pragma("unroll") for (int k = 0; k < 2; ++k) \
;         acc[ai][bj][m][n] = __builtin_amdgcn_mfma_f32_16x16x32_bf16(Bt[n][k], At[m][k], acc[ai][bj][m][n], 0, 0, 0); __builtin_amdgcn_s_setprio(0); } while (0)
; #define PG8_WAIT_V(n) asm volatile("s_waitcnt vmcnt(" #n ")" ::: "memory")
; #define PG8_WAIT_L(n) asm volatile("s_waitcnt lgkmcnt(" #n ")" ::: "memory")
; #define PG8_BAR __builtin_amdgcn_s_barrier()
; #define PG8_SCHED __builtin_amdgcn_sched_barrier(0)
; template <class Epi, class Sched, bool ALIGN_EPI = false, bool SP2 = false>
; __device__ __forceinline__ void gemm_phase(PG8_LAS unsigned char* lds, const Gemm g, const Sched& S, const Epi& E) {
;     ...
;             PG8_LDB(B0, 0, 0); PG8_LDB(B1, 0, 1); PG8_SCHED; PG8_LDA(At, 0, 0); PG8_STAGE(PG8_SA(1, 1), a1 + hstep, voffA);
;             PG8_WAIT_V(8); PG8_WAIT_L(0); PG8_BAR; PG8_MMA(0, 0, At, B0); PG8_MMA(0, 1, At, B1); PG8_BAR; PG8_SCHED;
;             PG8_LDA(At, 0, 1); PG8_STAGE(PG8_SB(0, 0), b2, voffB); PG8_STAGE(PG8_SB(0, 1), b2 + hstep, voffB); PG8_STAGE(PG8_SA(0, 0), a2, voffA);
;             PG8_WAIT_V(8); PG8_WAIT_L(0); PG8_BAR; PG8_MMA(1, 0, At, B0); PG8_MMA(1, 1, At, B1); PG8_BAR; PG8_SCHED;
.LBB0_418:
	s_add_u32 s56, s40, 0xfff80080
	s_addc_u32 s57, s41, -1
	s_add_i32 s75, 0, 0x10000
	s_cmp_eq_u32 s74, 28
	s_cselect_b32 s59, s2, s57
	s_cselect_b32 s58, s3, s56
	v_add_u32_e32 v142, s75, v156
	s_cselect_b32 s57, s49, s73
	s_cselect_b32 s56, s51, s72
	s_add_i32 s78, 0, 0x14000
	ds_read_b128 v[152:155], v142
	ds_read_b128 v[160:163], v142 offset:1024
	ds_read_b128 v[164:167], v142 offset:2048
	ds_read_b128 v[182:185], v142 offset:3072
	v_add_u32_e32 v142, s78, v156
	ds_read_b128 v[186:189], v142
	ds_read_b128 v[190:193], v142 offset:1024
	ds_read_b128 v[194:197], v142 offset:2048
	ds_read_b128 v[198:201], v142 offset:3072
	v_lshl_add_u64 v[168:169], s[40:41], 0, v[150:151]
	s_add_i32 m0, s63, 0xc000
	ds_read_b128 v[202:205], v158
	ds_read_b128 v[206:209], v158 offset:1024
	ds_read_b128 v[214:217], v158 offset:2048
	ds_read_b128 v[218:221], v158 offset:3072
	ds_read_b128 v[222:225], v158 offset:4096
	ds_read_b128 v[226:229], v158 offset:5120
	ds_read_b128 v[230:233], v158 offset:6144
	ds_read_b128 v[234:237], v158 offset:7168
	global_load_lds_dwordx4 v[168:169], off
	v_lshl_add_u64 v[168:169], s[40:41], 0, v[136:137]
	s_add_i32 m0, s63, 0xe000
	s_nop 0
	global_load_lds_dwordx4 v[168:169], off
	s_waitcnt vmcnt(8)
	s_waitcnt lgkmcnt(0)
	s_cmp_eq_u32 s100, 15
	s_cbranch_scc0 .Lg1q_sp0
	s_barrier
	s_setprio 1
	s_waitcnt lgkmcnt(0)
	v_mfma_f32_16x16x32_bf16 v[126:129], v[152:155], v[202:205], v[126:129]
	v_mfma_f32_16x16x32_bf16 v[122:125], v[164:167], v[202:205], v[122:125]
	v_mfma_f32_16x16x32_bf16 v[110:113], v[152:155], v[214:217], v[110:113]
	v_mfma_f32_16x16x32_bf16 v[106:109], v[164:167], v[214:217], v[106:109]
	v_mfma_f32_16x16x32_bf16 v[94:97], v[152:155], v[222:225], v[94:97]
	v_mfma_f32_16x16x32_bf16 v[90:93], v[164:167], v[222:225], v[90:93]
	v_mfma_f32_16x16x32_bf16 v[78:81], v[152:155], v[230:233], v[78:81]
	v_mfma_f32_16x16x32_bf16 v[74:77], v[164:167], v[230:233], v[74:77]
	v_mfma_f32_16x16x32_bf16 v[126:129], v[160:163], v[206:209], v[126:129]
	v_mfma_f32_16x16x32_bf16 v[122:125], v[182:185], v[206:209], v[122:125]
	v_mfma_f32_16x16x32_bf16 v[110:113], v[160:163], v[218:221], v[110:113]
	v_mfma_f32_16x16x32_bf16 v[106:109], v[182:185], v[218:221], v[106:109]
	v_mfma_f32_16x16x32_bf16 v[94:97], v[160:163], v[226:229], v[94:97]
	v_mfma_f32_16x16x32_bf16 v[90:93], v[182:185], v[226:229], v[90:93]
	v_mfma_f32_16x16x32_bf16 v[78:81], v[160:163], v[234:237], v[78:81]
	v_mfma_f32_16x16x32_bf16 v[74:77], v[182:185], v[234:237], v[74:77]
	s_setprio 0
	s_setprio 1
	v_mfma_f32_16x16x32_bf16 v[118:121], v[186:189], v[202:205], v[118:121]
	v_mfma_f32_16x16x32_bf16 v[114:117], v[194:197], v[202:205], v[114:117]
	v_mfma_f32_16x16x32_bf16 v[102:105], v[186:189], v[214:217], v[102:105]
	v_mfma_f32_16x16x32_bf16 v[98:101], v[194:197], v[214:217], v[98:101]
	v_mfma_f32_16x16x32_bf16 v[86:89], v[186:189], v[222:225], v[86:89]
	v_mfma_f32_16x16x32_bf16 v[82:85], v[194:197], v[222:225], v[82:85]
	v_mfma_f32_16x16x32_bf16 v[70:73], v[186:189], v[230:233], v[70:73]
	v_mfma_f32_16x16x32_bf16 v[66:69], v[194:197], v[230:233], v[66:69]
	v_mfma_f32_16x16x32_bf16 v[118:121], v[190:193], v[206:209], v[118:121]
	v_mfma_f32_16x16x32_bf16 v[114:117], v[198:201], v[206:209], v[114:117]
	v_mfma_f32_16x16x32_bf16 v[102:105], v[190:193], v[218:221], v[102:105]
	v_mfma_f32_16x16x32_bf16 v[98:101], v[198:201], v[218:221], v[98:101]
	v_mfma_f32_16x16x32_bf16 v[86:89], v[190:193], v[226:229], v[86:89]
	v_mfma_f32_16x16x32_bf16 v[82:85], v[198:201], v[226:229], v[82:85]
	v_mfma_f32_16x16x32_bf16 v[70:73], v[190:193], v[234:237], v[70:73]
	v_mfma_f32_16x16x32_bf16 v[66:69], v[198:201], v[234:237], v[66:69]
	s_setprio 0
.Lg1q_join0:
	s_barrier
	s_add_i32 s75, s75, s62
	v_lshl_add_u64 v[168:169], s[56:57], 0, v[0:1]
	s_mov_b32 m0, s75
	ds_read_b128 v[202:205], v158 offset:16384
	ds_read_b128 v[206:209], v158 offset:17408
	ds_read_b128 v[214:217], v158 offset:18432
	ds_read_b128 v[218:221], v158 offset:19456
	ds_read_b128 v[222:225], v158 offset:20480
	ds_read_b128 v[226:229], v158 offset:21504
	ds_read_b128 v[230:233], v158 offset:22528
	ds_read_b128 v[234:237], v158 offset:23552
	global_load_lds_dwordx4 v[168:169], off
	s_add_i32 m0, s75, 0x2000
	s_add_u32 s76, s56, 0x80000
	v_lshl_add_u64 v[238:239], s[56:57], 0, v[130:131]
	s_addc_u32 s77, s57, 0
	s_add_i32 s75, s78, s62
	global_load_lds_dwordx4 v[238:239], off
	v_lshl_add_u64 v[240:241], s[76:77], 0, v[0:1]
	s_mov_b32 m0, s75
	v_lshl_add_u64 v[242:243], s[58:59], 0, v[132:133]
	global_load_lds_dwordx4 v[240:241], off
	v_lshl_add_u64 v[240:241], s[76:77], 0, v[130:131]
	s_add_i32 m0, s75, 0x2000
	s_nop 0
	global_load_lds_dwordx4 v[240:241], off
	v_lshl_add_u64 v[240:241], s[58:59], 0, v[134:135]
	s_mov_b32 m0, s63
	s_nop 0
	global_load_lds_dwordx4 v[240:241], off
	s_mov_b32 m0, s64
	s_nop 0
	global_load_lds_dwordx4 v[242:243], off
	s_waitcnt vmcnt(8)
	s_waitcnt lgkmcnt(0)
	s_cmp_eq_u32 s100, 15
	s_cbranch_scc0 .Lg1q_sp1
	s_barrier
; #define PG8_STAGE(bufoff, gbase, voff) do { _Pragma("unroll") for (int _i = 0; _i < 2; ++_i) \
;         __builtin_amdgcn_global_load_lds((const unsigned*)((const char*)(gbase) + (voff)[_i]), (PG8_LAS unsigned*)(lds + (bufoff) + ldsw + _i * 8192), 16, 0, 0); } while (0)
; #define PG8_LDA(dst, b, h) do { _Pragma("unroll") for (int m = 0; m < 4; ++m) _Pragma("unroll") for (int k = 0; k < 2; ++k) dst[m][k] = *(const PG8_LAS bf16x8*)(lds + PG8_SA(b, h) + aoff + m * 2048 + k * 1024); } while (0)
; #define PG8_LDB(dst, b, h) do { _Pragma("unroll") for (int n = 0; n < 2; ++n) _Pragma("unroll") for (int k = 0; k < 2; ++k) dst[n][k] = *(const PG8_LAS bf16x8*)(lds + PG8_SB(b, h) + boff + n * 2048 + k * 1024); } while (0)
; #define PG8_MMA(ai, bj, At, Bt) do { __builtin_amdgcn_s_setprio(1); _Pragma("unroll") for (int m = 0; m < 4; ++m) _Pragma("unroll") for (int n = 0; n < 2; ++n) _Pragma("unroll") for (int k = 0; k < 2; ++k) \
;         acc[ai][bj][m][n] = __builtin_amdgcn_mfma_f32_16x16x32_bf16(Bt[n][k], At[m][k], acc[ai][bj][m][n], 0, 0, 0); __builtin_amdgcn_s_setprio(0); } while (0)
; #define PG8_WAIT_V(n) asm volatile("s_waitcnt vmcnt(" #n ")" ::: "memory")
; #define PG8_WAIT_L(n) asm volatile("s_waitcnt lgkmcnt(" #n ")" ::: "memory")
; #define PG8_BAR __builtin_amdgcn_s_barrier()
; #define PG8_SCHED __builtin_amdgcn_sched_barrier(0)
; template <class Epi, class Sched, bool ALIGN_EPI = false, bool SP2 = false>
; __device__ __forceinline__ void gemm_phase(PG8_LAS unsigned char* lds, const Gemm g, const Sched& S, const Epi& E) {
;     ...
;             PG8_WAIT_V(8); PG8_WAIT_L(0); PG8_BAR; PG8_MMA(1, 0, At, B0); PG8_MMA(1, 1, At, B1); PG8_BAR; PG8_SCHED;
;             PG8_LDB(B0, 1, 0); PG8_LDB(B1, 1, 1); PG8_SCHED; PG8_LDA(At, 1, 0); PG8_STAGE(PG8_SA(0, 1), a2 + hstep, voffA);
;             PG8_WAIT_V(8); PG8_WAIT_L(0); PG8_BAR; PG8_MMA(0, 0, At, B0); PG8_MMA(0, 1, At, B1); PG8_BAR; PG8_SCHED;
	s_setprio 1
	s_waitcnt lgkmcnt(0)
	v_mfma_f32_16x16x32_bf16 v[62:65], v[152:155], v[202:205], v[62:65]
	v_mfma_f32_16x16x32_bf16 v[58:61], v[164:167], v[202:205], v[58:61]
	v_mfma_f32_16x16x32_bf16 v[46:49], v[152:155], v[214:217], v[46:49]
	v_mfma_f32_16x16x32_bf16 v[42:45], v[164:167], v[214:217], v[42:45]
	v_mfma_f32_16x16x32_bf16 v[30:33], v[152:155], v[222:225], v[30:33]
	v_mfma_f32_16x16x32_bf16 v[26:29], v[164:167], v[222:225], v[26:29]
	v_mfma_f32_16x16x32_bf16 v[14:17], v[152:155], v[230:233], v[14:17]
	v_mfma_f32_16x16x32_bf16 v[10:13], v[164:167], v[230:233], v[10:13]
	v_mfma_f32_16x16x32_bf16 v[62:65], v[160:163], v[206:209], v[62:65]
	v_mfma_f32_16x16x32_bf16 v[58:61], v[182:185], v[206:209], v[58:61]
	v_mfma_f32_16x16x32_bf16 v[46:49], v[160:163], v[218:221], v[46:49]
	v_mfma_f32_16x16x32_bf16 v[42:45], v[182:185], v[218:221], v[42:45]
	v_mfma_f32_16x16x32_bf16 v[30:33], v[160:163], v[226:229], v[30:33]
	v_mfma_f32_16x16x32_bf16 v[26:29], v[182:185], v[226:229], v[26:29]
	v_mfma_f32_16x16x32_bf16 v[14:17], v[160:163], v[234:237], v[14:17]
	v_mfma_f32_16x16x32_bf16 v[10:13], v[182:185], v[234:237], v[10:13]
	s_setprio 0
	s_setprio 1
	v_mfma_f32_16x16x32_bf16 v[54:57], v[186:189], v[202:205], v[54:57]
	v_mfma_f32_16x16x32_bf16 v[50:53], v[194:197], v[202:205], v[50:53]
	v_mfma_f32_16x16x32_bf16 v[38:41], v[186:189], v[214:217], v[38:41]
	v_mfma_f32_16x16x32_bf16 v[34:37], v[194:197], v[214:217], v[34:37]
	v_mfma_f32_16x16x32_bf16 v[22:25], v[186:189], v[222:225], v[22:25]
	v_mfma_f32_16x16x32_bf16 v[18:21], v[194:197], v[222:225], v[18:21]
	v_mfma_f32_16x16x32_bf16 v[6:9], v[186:189], v[230:233], v[6:9]
	v_mfma_f32_16x16x32_bf16 v[2:5], v[194:197], v[230:233], v[2:5]
	v_mfma_f32_16x16x32_bf16 v[54:57], v[190:193], v[206:209], v[54:57]
	v_mfma_f32_16x16x32_bf16 v[50:53], v[198:201], v[206:209], v[50:53]
	v_mfma_f32_16x16x32_bf16 v[38:41], v[190:193], v[218:221], v[38:41]
	v_mfma_f32_16x16x32_bf16 v[34:37], v[198:201], v[218:221], v[34:37]
	v_mfma_f32_16x16x32_bf16 v[22:25], v[190:193], v[226:229], v[22:25]
	v_mfma_f32_16x16x32_bf16 v[18:21], v[198:201], v[226:229], v[18:21]
	v_mfma_f32_16x16x32_bf16 v[6:9], v[190:193], v[234:237], v[6:9]
	v_mfma_f32_16x16x32_bf16 v[2:5], v[198:201], v[234:237], v[2:5]
	s_setprio 0
.Lg1q_join1:
	s_barrier
	s_add_i32 s75, 0, 0x18000
	v_add_u32_e32 v142, s75, v156
	s_add_i32 s76, 0, 0x1c000
	ds_read_b128 v[152:155], v142
	ds_read_b128 v[160:163], v142 offset:1024
	ds_read_b128 v[164:167], v142 offset:2048
	ds_read_b128 v[182:185], v142 offset:3072
	v_add_u32_e32 v142, s76, v156
	ds_read_b128 v[186:189], v142
	ds_read_b128 v[190:193], v142 offset:1024
	ds_read_b128 v[194:197], v142 offset:2048
	ds_read_b128 v[198:201], v142 offset:3072
	s_add_u32 s58, s58, 0x80000
	s_addc_u32 s59, s59, 0
	s_mov_b32 m0, s65
	v_lshl_add_u64 v[244:245], s[58:59], 0, v[134:135]
	ds_read_b128 v[202:205], v158 offset:32768
	ds_read_b128 v[206:209], v158 offset:33792
	ds_read_b128 v[214:217], v158 offset:34816
	ds_read_b128 v[218:221], v158 offset:35840
	ds_read_b128 v[222:225], v158 offset:36864
	ds_read_b128 v[226:229], v158 offset:37888
	ds_read_b128 v[230:233], v158 offset:38912
	ds_read_b128 v[234:237], v158 offset:39936
	global_load_lds_dwordx4 v[244:245], off
	v_lshl_add_u64 v[244:245], s[58:59], 0, v[132:133]
	s_mov_b32 m0, s66
	s_nop 0
	global_load_lds_dwordx4 v[244:245], off
	s_waitcnt vmcnt(8)
	s_waitcnt lgkmcnt(0)
	s_cmp_eq_u32 s100, 15
	s_cbranch_scc0 .Lg1q_sp2
	s_barrier
	s_setprio 1
	s_waitcnt lgkmcnt(0)
	v_mfma_f32_16x16x32_bf16 v[126:129], v[152:155], v[202:205], v[126:129]
	v_mfma_f32_16x16x32_bf16 v[122:125], v[164:167], v[202:205], v[122:125]
	v_mfma_f32_16x16x32_bf16 v[110:113], v[152:155], v[214:217], v[110:113]
	v_mfma_f32_16x16x32_bf16 v[106:109], v[164:167], v[214:217], v[106:109]
	v_mfma_f32_16x16x32_bf16 v[94:97], v[152:155], v[222:225], v[94:97]
	v_mfma_f32_16x16x32_bf16 v[90:93], v[164:167], v[222:225], v[90:93]
	v_mfma_f32_16x16x32_bf16 v[78:81], v[152:155], v[230:233], v[78:81]
	v_mfma_f32_16x16x32_bf16 v[74:77], v[164:167], v[230:233], v[74:77]
	v_mfma_f32_16x16x32_bf16 v[126:129], v[160:163], v[206:209], v[126:129]
	v_mfma_f32_16x16x32_bf16 v[122:125], v[182:185], v[206:209], v[122:125]
	v_mfma_f32_16x16x32_bf16 v[110:113], v[160:163], v[218:221], v[110:113]
	v_mfma_f32_16x16x32_bf16 v[106:109], v[182:185], v[218:221], v[106:109]
	v_mfma_f32_16x16x32_bf16 v[94:97], v[160:163], v[226:229], v[94:97]
	v_mfma_f32_16x16x32_bf16 v[90:93], v[182:185], v[226:229], v[90:93]
	v_mfma_f32_16x16x32_bf16 v[78:81], v[160:163], v[234:237], v[78:81]
	v_mfma_f32_16x16x32_bf16 v[74:77], v[182:185], v[234:237], v[74:77]
	s_setprio 0
	s_setprio 1
	v_mfma_f32_16x16x32_bf16 v[118:121], v[186:189], v[202:205], v[118:121]
	v_mfma_f32_16x16x32_bf16 v[114:117], v[194:197], v[202:205], v[114:117]
	v_mfma_f32_16x16x32_bf16 v[102:105], v[186:189], v[214:217], v[102:105]
	v_mfma_f32_16x16x32_bf16 v[98:101], v[194:197], v[214:217], v[98:101]
	v_mfma_f32_16x16x32_bf16 v[86:89], v[186:189], v[222:225], v[86:89]
	v_mfma_f32_16x16x32_bf16 v[82:85], v[194:197], v[222:225], v[82:85]
	v_mfma_f32_16x16x32_bf16 v[70:73], v[186:189], v[230:233], v[70:73]
	v_mfma_f32_16x16x32_bf16 v[66:69], v[194:197], v[230:233], v[66:69]
	v_mfma_f32_16x16x32_bf16 v[118:121], v[190:193], v[206:209], v[118:121]
	v_mfma_f32_16x16x32_bf16 v[114:117], v[198:201], v[206:209], v[114:117]
	v_mfma_f32_16x16x32_bf16 v[102:105], v[190:193], v[218:221], v[102:105]
	v_mfma_f32_16x16x32_bf16 v[98:101], v[198:201], v[218:221], v[98:101]
	v_mfma_f32_16x16x32_bf16 v[86:89], v[190:193], v[226:229], v[86:89]
	v_mfma_f32_16x16x32_bf16 v[82:85], v[198:201], v[226:229], v[82:85]
	v_mfma_f32_16x16x32_bf16 v[70:73], v[190:193], v[234:237], v[70:73]
	v_mfma_f32_16x16x32_bf16 v[66:69], v[198:201], v[234:237], v[66:69]
	s_setprio 0
; #define PG8_STAGE(bufoff, gbase, voff) do { _Pragma("unroll") for (int _i = 0; _i < 2; ++_i) \
;         __builtin_amdgcn_global_load_lds((const unsigned*)((const char*)(gbase) + (voff)[_i]), (PG8_LAS unsigned*)(lds + (bufoff) + ldsw + _i * 8192), 16, 0, 0); } while (0)
; #define PG8_LDA(dst, b, h) do { _Pragma("unroll") for (int m = 0; m < 4; ++m) _Pragma("unroll") for (int k = 0; k < 2; ++k) dst[m][k] = *(const PG8_LAS bf16x8*)(lds + PG8_SA(b, h) + aoff + m * 2048 + k * 1024); } while (0)
; #define PG8_MMA(ai, bj, At, Bt) do { __builtin_amdgcn_s_setprio(1); _Pragma("unroll") for (int m = 0; m < 4; ++m) _Pragma("unroll") for (int n = 0; n < 2; ++n) _Pragma("unroll") for (int k = 0; k < 2; ++k) \
;         acc[ai][bj][m][n] = __builtin_amdgcn_mfma_f32_16x16x32_bf16(Bt[n][k], At[m][k], acc[ai][bj][m][n], 0, 0, 0); __builtin_amdgcn_s_setprio(0); } while (0)
; #define PG8_WAIT_V(n) asm volatile("s_waitcnt vmcnt(" #n ")" ::: "memory")
; #define PG8_WAIT_L(n) asm volatile("s_waitcnt lgkmcnt(" #n ")" ::: "memory")
; #define PG8_BAR __builtin_amdgcn_s_barrier()
; #define PG8_SCHED __builtin_amdgcn_sched_barrier(0)
; template <class Epi, class Sched, bool ALIGN_EPI = false, bool SP2 = false>
; __device__ __forceinline__ void gemm_phase(PG8_LAS unsigned char* lds, const Gemm g, const Sched& S, const Epi& E) {
;     ...
;             PG8_WAIT_V(8); PG8_WAIT_L(0); PG8_BAR; PG8_MMA(0, 0, At, B0); PG8_MMA(0, 1, At, B1); PG8_BAR; PG8_SCHED;
;             PG8_LDA(At, 1, 1); PG8_STAGE(PG8_SB(1, 0), b3, voffB); PG8_STAGE(PG8_SB(1, 1), b3 + hstep, voffB); PG8_STAGE(PG8_SA(1, 0), a3, voffA);
;             PG8_WAIT_V(8); PG8_WAIT_L(0); PG8_BAR; PG8_MMA(1, 0, At, B0); PG8_MMA(1, 1, At, B1); PG8_BAR; PG8_SCHED;
.Lg1q_join2:
	s_barrier
	s_add_i32 s58, s75, s62
	v_lshl_add_u64 v[168:169], v[168:169], 0, s[34:35]
	s_mov_b32 m0, s58
	ds_read_b128 v[202:205], v158 offset:49152
	ds_read_b128 v[206:209], v158 offset:50176
	ds_read_b128 v[214:217], v158 offset:51200
	ds_read_b128 v[218:221], v158 offset:52224
	ds_read_b128 v[222:225], v158 offset:53248
	ds_read_b128 v[226:229], v158 offset:54272
	ds_read_b128 v[230:233], v158 offset:55296
	ds_read_b128 v[234:237], v158 offset:56320
	global_load_lds_dwordx4 v[168:169], off
	s_add_i32 m0, s58, 0x2000
	s_add_u32 s56, s56, 0x80080
	v_lshl_add_u64 v[168:169], v[238:239], 0, s[34:35]
	s_addc_u32 s57, s57, 0
	s_add_i32 s58, s76, s62
	global_load_lds_dwordx4 v[168:169], off
	v_lshl_add_u64 v[168:169], s[56:57], 0, v[0:1]
	s_mov_b32 m0, s58
	s_nop 0
	global_load_lds_dwordx4 v[168:169], off
	v_lshl_add_u64 v[168:169], s[56:57], 0, v[130:131]
	s_add_i32 m0, s58, 0x2000
	s_nop 0
	global_load_lds_dwordx4 v[168:169], off
	v_lshl_add_u64 v[168:169], v[240:241], 0, s[34:35]
	s_mov_b32 m0, s67
	s_nop 0
	global_load_lds_dwordx4 v[168:169], off
	v_lshl_add_u64 v[168:169], v[242:243], 0, s[34:35]
	s_mov_b32 m0, s68
	s_nop 0
	global_load_lds_dwordx4 v[168:169], off
	s_waitcnt vmcnt(8)
	s_waitcnt lgkmcnt(0)
	s_cmp_eq_u32 s100, 15
	s_cbranch_scc0 .Lg1q_sp3
	s_barrier
	s_setprio 1
	s_waitcnt lgkmcnt(0)
	v_mfma_f32_16x16x32_bf16 v[62:65], v[152:155], v[202:205], v[62:65]
	v_mfma_f32_16x16x32_bf16 v[58:61], v[164:167], v[202:205], v[58:61]
	v_mfma_f32_16x16x32_bf16 v[46:49], v[152:155], v[214:217], v[46:49]
	v_mfma_f32_16x16x32_bf16 v[42:45], v[164:167], v[214:217], v[42:45]
	v_mfma_f32_16x16x32_bf16 v[30:33], v[152:155], v[222:225], v[30:33]
	v_mfma_f32_16x16x32_bf16 v[26:29], v[164:167], v[222:225], v[26:29]
	v_mfma_f32_16x16x32_bf16 v[14:17], v[152:155], v[230:233], v[14:17]
	v_mfma_f32_16x16x32_bf16 v[10:13], v[164:167], v[230:233], v[10:13]
	v_mfma_f32_16x16x32_bf16 v[62:65], v[160:163], v[206:209], v[62:65]
	v_mfma_f32_16x16x32_bf16 v[58:61], v[182:185], v[206:209], v[58:61]
	v_mfma_f32_16x16x32_bf16 v[46:49], v[160:163], v[218:221], v[46:49]
	v_mfma_f32_16x16x32_bf16 v[42:45], v[182:185], v[218:221], v[42:45]
	v_mfma_f32_16x16x32_bf16 v[30:33], v[160:163], v[226:229], v[30:33]
	v_mfma_f32_16x16x32_bf16 v[26:29], v[182:185], v[226:229], v[26:29]
	v_mfma_f32_16x16x32_bf16 v[14:17], v[160:163], v[234:237], v[14:17]
	v_mfma_f32_16x16x32_bf16 v[10:13], v[182:185], v[234:237], v[10:13]
	s_setprio 0
	s_setprio 1
	v_mfma_f32_16x16x32_bf16 v[54:57], v[186:189], v[202:205], v[54:57]
	v_mfma_f32_16x16x32_bf16 v[50:53], v[194:197], v[202:205], v[50:53]
	v_mfma_f32_16x16x32_bf16 v[38:41], v[186:189], v[214:217], v[38:41]
	v_mfma_f32_16x16x32_bf16 v[34:37], v[194:197], v[214:217], v[34:37]
	v_mfma_f32_16x16x32_bf16 v[22:25], v[186:189], v[222:225], v[22:25]
	v_mfma_f32_16x16x32_bf16 v[18:21], v[194:197], v[222:225], v[18:21]
	v_mfma_f32_16x16x32_bf16 v[6:9], v[186:189], v[230:233], v[6:9]
	v_mfma_f32_16x16x32_bf16 v[2:5], v[194:197], v[230:233], v[2:5]
	v_mfma_f32_16x16x32_bf16 v[54:57], v[190:193], v[206:209], v[54:57]
	v_mfma_f32_16x16x32_bf16 v[50:53], v[198:201], v[206:209], v[50:53]
	v_mfma_f32_16x16x32_bf16 v[38:41], v[190:193], v[218:221], v[38:41]
	v_mfma_f32_16x16x32_bf16 v[34:37], v[198:201], v[218:221], v[34:37]
	v_mfma_f32_16x16x32_bf16 v[22:25], v[190:193], v[226:229], v[22:25]
	v_mfma_f32_16x16x32_bf16 v[18:21], v[198:201], v[226:229], v[18:21]
	v_mfma_f32_16x16x32_bf16 v[6:9], v[190:193], v[234:237], v[6:9]
	v_mfma_f32_16x16x32_bf16 v[2:5], v[198:201], v[234:237], v[2:5]
	s_setprio 0
.Lg1q_join3:
	s_barrier
	s_add_i32 s74, s74, 2
	s_add_u32 s72, s72, 0x100
	s_addc_u32 s73, s73, 0
	s_add_u32 s40, s40, 0x100
	s_addc_u32 s41, s41, 0
	s_cmp_gt_u32 s74, 29
	s_cbranch_scc0 .LBB0_418
	s_and_b64 vcc, exec, s[44:45]
	s_cbranch_vccz .LBB0_421
	s_barrier

; __device__ __forceinline__ unsigned cvt_pk_bf16(float lo, float hi) { unsigned r; asm volatile("v_cvt_pk_bf16_f32 %0, %1, %2" : "=v"(r) : "v"(lo), "v"(hi)); return r; }
; __device__ __forceinline__ float fsig(float x) { return __builtin_amdgcn_rcpf(1.0f + __expf(-x)); }
;     __device__ __forceinline__ void operator()(const f32x4 (&acc)[2][2][4][2], const Unit& u, int wr, int wc, int fr, int fq) const {
;         const int pn = u.pn;
;         const int act = (pn >= 33) ? 2 : 0;
;         const int row0 = u.pm * BM + wr * 64 + fr, col0 = pn * BM + wc * 32 + 8 * fq;
; #pragma unroll
;         for (int ai = 0; ai < 2; ++ai)
; #pragma unroll
;             for (int m = 0; m < 4; ++m) { bf16_t* rowp = O + (size_t)(row0 + ai * HALF + m * 16) * LDP + col0;
; #pragma unroll
;                 for (int bj = 0; bj < 2; ++bj) { f32x4 v0 = acc[ai][bj][m][0], v1 = acc[ai][bj][m][1];
;                     if (act == 1) {
; #pragma unroll
;                         for (int j = 0; j < 4; ++j) { v0[j] = v0[j] * fsig(v0[j]); v1[j] = v1[j] * fsig(v1[j]); } }
;                     else if (act == 2) {
; #pragma unroll
;                         for (int j = 0; j < 4; ++j) { v0[j] = fsig(v0[j]); v1[j] = fsig(v1[j]); } }
;                     u32x4 w; w.x = cvt_pk_bf16(v0[0], v0[1]); w.y = cvt_pk_bf16(v0[2], v0[3]); w.z = cvt_pk_bf16(v1[0], v1[1]); w.w = cvt_pk_bf16(v1[2], v1[3]);
;                     *(u32x4*)(rowp + bj * HALF) = w; } }
.LBB0_423:
	v_lshl_add_u32 v159, s71, 8, v138
	v_lshl_or_b32 v152, s70, 8, v157
	v_mov_b64_e32 v[154:155], s[42:43]
	v_ashrrev_i32_e32 v153, 31, v152
	v_mad_i64_i32 v[154:155], s[2:3], v159, s7, v[154:155]
	v_cvt_pk_bf16_f32 v126, v126, v127
	v_cvt_pk_bf16_f32 v127, v128, v129
	v_cvt_pk_bf16_f32 v128, v122, v123
	v_cndmask_b32_e64 v122, 0, 1, s[56:57]
	v_lshl_add_u64 v[154:155], v[152:153], 1, v[154:155]
	v_cmp_ne_u32_e64 s[40:41], 1, v122
	s_andn2_b64 vcc, exec, s[56:57]
	v_cvt_pk_bf16_f32 v129, v124, v125
	s_bitcmp1_b32 s100, 0
	s_cselect_b64 exec, -1, 0
	flat_store_dwordx4 v[154:155], v[126:129]
	s_mov_b64 exec, -1
	s_cbranch_vccnz .LBB0_425
	v_mul_f32_e32 v118, 0xbfb8aa3b, v118
	v_mul_f32_e32 v114, 0xbfb8aa3b, v114
	v_mul_f32_e32 v119, 0xbfb8aa3b, v119
	v_mul_f32_e32 v115, 0xbfb8aa3b, v115
	v_mul_f32_e32 v120, 0xbfb8aa3b, v120
	v_mul_f32_e32 v116, 0xbfb8aa3b, v116
	v_mul_f32_e32 v121, 0xbfb8aa3b, v121
	v_mul_f32_e32 v117, 0xbfb8aa3b, v117
	v_exp_f32_e32 v118, v118
	v_exp_f32_e32 v114, v114
	v_exp_f32_e32 v119, v119
	v_exp_f32_e32 v115, v115
	v_exp_f32_e32 v120, v120
	v_exp_f32_e32 v116, v116
	v_exp_f32_e32 v121, v121
	v_exp_f32_e32 v117, v117
	v_add_f32_e32 v118, 1.0, v118
	v_add_f32_e32 v114, 1.0, v114
	v_add_f32_e32 v119, 1.0, v119
	v_add_f32_e32 v115, 1.0, v115
	v_add_f32_e32 v120, 1.0, v120
	v_add_f32_e32 v116, 1.0, v116
	v_add_f32_e32 v121, 1.0, v121
	v_add_f32_e32 v117, 1.0, v117
	v_rcp_f32_e32 v118, v118
	v_rcp_f32_e32 v114, v114
	v_rcp_f32_e32 v119, v119
	v_rcp_f32_e32 v115, v115
	v_rcp_f32_e32 v120, v120
	v_rcp_f32_e32 v116, v116
	v_rcp_f32_e32 v121, v121
	v_rcp_f32_e32 v117, v117
.LBB0_425:
	v_readlane_b32 s78, v253, 49
	s_and_b64 vcc, exec, s[40:41]
	s_mov_b32 s75, 0x800000
	s_mov_b32 s76, 0x1ffff
	v_readlane_b32 s79, v253, 50
	v_cvt_pk_bf16_f32 v118, v118, v119
	v_cvt_pk_bf16_f32 v119, v120, v121
	v_cvt_pk_bf16_f32 v120, v114, v115
	v_cvt_pk_bf16_f32 v121, v116, v117
	s_bitcmp1_b32 s100, 1
	s_cselect_b64 exec, -1, 0
	flat_store_dwordx4 v[154:155], v[118:121] offset:256
	s_mov_b64 exec, -1
	s_cbranch_vccnz .LBB0_427
	v_mul_f32_e32 v110, 0xbfb8aa3b, v110
	v_mul_f32_e32 v106, 0xbfb8aa3b, v106
	v_mul_f32_e32 v111, 0xbfb8aa3b, v111
	v_mul_f32_e32 v107, 0xbfb8aa3b, v107
	v_mul_f32_e32 v112, 0xbfb8aa3b, v112
	v_mul_f32_e32 v108, 0xbfb8aa3b, v108
	v_mul_f32_e32 v113, 0xbfb8aa3b, v113
	v_mul_f32_e32 v109, 0xbfb8aa3b, v109
	v_exp_f32_e32 v110, v110
	v_exp_f32_e32 v106, v106
	v_exp_f32_e32 v111, v111
	v_exp_f32_e32 v107, v107
	v_exp_f32_e32 v112, v112
	v_exp_f32_e32 v108, v108
	v_exp_f32_e32 v113, v113
	v_exp_f32_e32 v109, v109
	v_add_f32_e32 v110, 1.0, v110
	v_add_f32_e32 v106, 1.0, v106
	v_add_f32_e32 v111, 1.0, v111
	v_add_f32_e32 v107, 1.0, v107
	v_add_f32_e32 v112, 1.0, v112
	v_add_f32_e32 v108, 1.0, v108
	v_add_f32_e32 v113, 1.0, v113
	v_add_f32_e32 v109, 1.0, v109
	v_rcp_f32_e32 v110, v110
	v_rcp_f32_e32 v106, v106
	v_rcp_f32_e32 v111, v111
	v_rcp_f32_e32 v107, v107
	v_rcp_f32_e32 v112, v112
	v_rcp_f32_e32 v108, v108
	v_rcp_f32_e32 v113, v113
	v_rcp_f32_e32 v109, v109
.LBB0_427:
	v_or_b32_e32 v116, 16, v159
	v_mov_b64_e32 v[114:115], s[42:43]
	v_mad_i64_i32 v[114:115], s[2:3], v116, s7, v[114:115]
	v_lshl_add_u64 v[114:115], v[152:153], 1, v[114:115]
	s_and_b64 vcc, exec, s[40:41]
	v_cvt_pk_bf16_f32 v110, v110, v111
	v_cvt_pk_bf16_f32 v111, v112, v113
	v_cvt_pk_bf16_f32 v112, v106, v107
	v_cvt_pk_bf16_f32 v113, v108, v109
	s_bitcmp1_b32 s100, 0
	s_cselect_b64 exec, -1, 0
	flat_store_dwordx4 v[114:115], v[110:113]
	s_mov_b64 exec, -1
	s_cbranch_vccnz .LBB0_429
	v_mul_f32_e32 v102, 0xbfb8aa3b, v102
	v_mul_f32_e32 v98, 0xbfb8aa3b, v98
	v_mul_f32_e32 v103, 0xbfb8aa3b, v103
	v_mul_f32_e32 v99, 0xbfb8aa3b, v99
	v_mul_f32_e32 v104, 0xbfb8aa3b, v104
	v_mul_f32_e32 v100, 0xbfb8aa3b, v100
	v_mul_f32_e32 v105, 0xbfb8aa3b, v105
	v_mul_f32_e32 v101, 0xbfb8aa3b, v101
	v_exp_f32_e32 v102, v102
	v_exp_f32_e32 v98, v98
	v_exp_f32_e32 v103, v103
	v_exp_f32_e32 v99, v99
	v_exp_f32_e32 v104, v104
	v_exp_f32_e32 v100, v100
	v_exp_f32_e32 v105, v105
	v_exp_f32_e32 v101, v101
	v_add_f32_e32 v102, 1.0, v102
	v_add_f32_e32 v98, 1.0, v98
	v_add_f32_e32 v103, 1.0, v103
	v_add_f32_e32 v99, 1.0, v99
	v_add_f32_e32 v104, 1.0, v104
	v_add_f32_e32 v100, 1.0, v100
	v_add_f32_e32 v105, 1.0, v105
	v_add_f32_e32 v101, 1.0, v101
	v_rcp_f32_e32 v102, v102
	v_rcp_f32_e32 v98, v98
	v_rcp_f32_e32 v103, v103
	v_rcp_f32_e32 v99, v99
	v_rcp_f32_e32 v104, v104
	v_rcp_f32_e32 v100, v100
	v_rcp_f32_e32 v105, v105
	v_rcp_f32_e32 v101, v101
.LBB0_429:
	s_and_b64 vcc, exec, s[40:41]
	v_cvt_pk_bf16_f32 v102, v102, v103
	v_cvt_pk_bf16_f32 v103, v104, v105
	v_cvt_pk_bf16_f32 v104, v98, v99
	v_cvt_pk_bf16_f32 v105, v100, v101
	s_bitcmp1_b32 s100, 1
	s_cselect_b64 exec, -1, 0
	flat_store_dwordx4 v[114:115], v[102:105] offset:256
	s_mov_b64 exec, -1
	s_cbranch_vccnz .LBB0_431
	v_mul_f32_e32 v94, 0xbfb8aa3b, v94
	v_mul_f32_e32 v90, 0xbfb8aa3b, v90
	v_mul_f32_e32 v95, 0xbfb8aa3b, v95
	v_mul_f32_e32 v91, 0xbfb8aa3b, v91
	v_mul_f32_e32 v96, 0xbfb8aa3b, v96
	v_mul_f32_e32 v92, 0xbfb8aa3b, v92
	v_mul_f32_e32 v97, 0xbfb8aa3b, v97
	v_mul_f32_e32 v93, 0xbfb8aa3b, v93
	v_exp_f32_e32 v94, v94
	v_exp_f32_e32 v90, v90
	v_exp_f32_e32 v95, v95
	v_exp_f32_e32 v91, v91
	v_exp_f32_e32 v96, v96
	v_exp_f32_e32 v92, v92
	v_exp_f32_e32 v97, v97
	v_exp_f32_e32 v93, v93
	v_add_f32_e32 v94, 1.0, v94
	v_add_f32_e32 v90, 1.0, v90
	v_add_f32_e32 v95, 1.0, v95
	v_add_f32_e32 v91, 1.0, v91
	v_add_f32_e32 v96, 1.0, v96
	v_add_f32_e32 v92, 1.0, v92
	v_add_f32_e32 v97, 1.0, v97
	v_add_f32_e32 v93, 1.0, v93
	v_rcp_f32_e32 v94, v94
	v_rcp_f32_e32 v90, v90
	v_rcp_f32_e32 v95, v95
	v_rcp_f32_e32 v91, v91
	v_rcp_f32_e32 v96, v96
	v_rcp_f32_e32 v92, v92
	v_rcp_f32_e32 v97, v97
	v_rcp_f32_e32 v93, v93
; __device__ __forceinline__ unsigned cvt_pk_bf16(float lo, float hi) { unsigned r; asm volatile("v_cvt_pk_bf16_f32 %0, %1, %2" : "=v"(r) : "v"(lo), "v"(hi)); return r; }
; __device__ __forceinline__ float fsig(float x) { return __builtin_amdgcn_rcpf(1.0f + __expf(-x)); }
;     __device__ __forceinline__ void operator()(const f32x4 (&acc)[2][2][4][2], const Unit& u, int wr, int wc, int fr, int fq) const {
;     ...
;             for (int m = 0; m < 4; ++m) { bf16_t* rowp = O + (size_t)(row0 + ai * HALF + m * 16) * LDP + col0;
; #pragma unroll
;                 for (int bj = 0; bj < 2; ++bj) { f32x4 v0 = acc[ai][bj][m][0], v1 = acc[ai][bj][m][1];
;                     if (act == 1) {
; #pragma unroll
;                         for (int j = 0; j < 4; ++j) { v0[j] = v0[j] * fsig(v0[j]); v1[j] = v1[j] * fsig(v1[j]); } }
;                     else if (act == 2) {
; #pragma unroll
;                         for (int j = 0; j < 4; ++j) { v0[j] = fsig(v0[j]); v1[j] = fsig(v1[j]); } }
;                     u32x4 w; w.x = cvt_pk_bf16(v0[0], v0[1]); w.y = cvt_pk_bf16(v0[2], v0[3]); w.z = cvt_pk_bf16(v1[0], v1[1]); w.w = cvt_pk_bf16(v1[2], v1[3]);
;                     *(u32x4*)(rowp + bj * HALF) = w; } }
.LBB0_431:
	v_or_b32_e32 v100, 32, v159
	v_mov_b64_e32 v[98:99], s[42:43]
	v_mad_i64_i32 v[98:99], s[2:3], v100, s7, v[98:99]
	v_lshl_add_u64 v[98:99], v[152:153], 1, v[98:99]
	s_and_b64 vcc, exec, s[40:41]
	v_cvt_pk_bf16_f32 v94, v94, v95
	v_cvt_pk_bf16_f32 v95, v96, v97
	v_cvt_pk_bf16_f32 v96, v90, v91
	v_cvt_pk_bf16_f32 v97, v92, v93
	s_bitcmp1_b32 s100, 0
	s_cselect_b64 exec, -1, 0
	flat_store_dwordx4 v[98:99], v[94:97]
	s_mov_b64 exec, -1
	s_cbranch_vccnz .LBB0_433
	v_mul_f32_e32 v86, 0xbfb8aa3b, v86
	v_mul_f32_e32 v82, 0xbfb8aa3b, v82
	v_mul_f32_e32 v87, 0xbfb8aa3b, v87
	v_mul_f32_e32 v83, 0xbfb8aa3b, v83
	v_mul_f32_e32 v88, 0xbfb8aa3b, v88
	v_mul_f32_e32 v84, 0xbfb8aa3b, v84
	v_mul_f32_e32 v89, 0xbfb8aa3b, v89
	v_mul_f32_e32 v85, 0xbfb8aa3b, v85
	v_exp_f32_e32 v86, v86
	v_exp_f32_e32 v82, v82
	v_exp_f32_e32 v87, v87
	v_exp_f32_e32 v83, v83
	v_exp_f32_e32 v88, v88
	v_exp_f32_e32 v84, v84
	v_exp_f32_e32 v89, v89
	v_exp_f32_e32 v85, v85
	v_add_f32_e32 v86, 1.0, v86
	v_add_f32_e32 v82, 1.0, v82
	v_add_f32_e32 v87, 1.0, v87
	v_add_f32_e32 v83, 1.0, v83
	v_add_f32_e32 v88, 1.0, v88
	v_add_f32_e32 v84, 1.0, v84
	v_add_f32_e32 v89, 1.0, v89
	v_add_f32_e32 v85, 1.0, v85
	v_rcp_f32_e32 v86, v86
	v_rcp_f32_e32 v82, v82
	v_rcp_f32_e32 v87, v87
	v_rcp_f32_e32 v83, v83
	v_rcp_f32_e32 v88, v88
	v_rcp_f32_e32 v84, v84
	v_rcp_f32_e32 v89, v89
	v_rcp_f32_e32 v85, v85
.LBB0_433:
	s_and_b64 vcc, exec, s[40:41]
	v_cvt_pk_bf16_f32 v86, v86, v87
	v_cvt_pk_bf16_f32 v87, v88, v89
	v_cvt_pk_bf16_f32 v88, v82, v83
	v_cvt_pk_bf16_f32 v89, v84, v85
	s_bitcmp1_b32 s100, 1
	s_cselect_b64 exec, -1, 0
	flat_store_dwordx4 v[98:99], v[86:89] offset:256
	s_mov_b64 exec, -1
	s_cbranch_vccnz .LBB0_435
	v_mul_f32_e32 v78, 0xbfb8aa3b, v78
	v_mul_f32_e32 v74, 0xbfb8aa3b, v74
	v_mul_f32_e32 v79, 0xbfb8aa3b, v79
	v_mul_f32_e32 v75, 0xbfb8aa3b, v75
	v_mul_f32_e32 v80, 0xbfb8aa3b, v80
	v_mul_f32_e32 v76, 0xbfb8aa3b, v76
	v_mul_f32_e32 v81, 0xbfb8aa3b, v81
	v_mul_f32_e32 v77, 0xbfb8aa3b, v77
	v_exp_f32_e32 v78, v78
	v_exp_f32_e32 v74, v74
	v_exp_f32_e32 v79, v79
	v_exp_f32_e32 v75, v75
	v_exp_f32_e32 v80, v80
	v_exp_f32_e32 v76, v76
	v_exp_f32_e32 v81, v81
	v_exp_f32_e32 v77, v77
	v_add_f32_e32 v78, 1.0, v78
	v_add_f32_e32 v74, 1.0, v74
	v_add_f32_e32 v79, 1.0, v79
	v_add_f32_e32 v75, 1.0, v75
	v_add_f32_e32 v80, 1.0, v80
	v_add_f32_e32 v76, 1.0, v76
	v_add_f32_e32 v81, 1.0, v81
	v_add_f32_e32 v77, 1.0, v77
	v_rcp_f32_e32 v78, v78
	v_rcp_f32_e32 v74, v74
	v_rcp_f32_e32 v79, v79
	v_rcp_f32_e32 v75, v75
	v_rcp_f32_e32 v80, v80
	v_rcp_f32_e32 v76, v76
	v_rcp_f32_e32 v81, v81
	v_rcp_f32_e32 v77, v77
.LBB0_435:
	v_or_b32_e32 v84, 48, v159
	v_mov_b64_e32 v[82:83], s[42:43]
	v_mad_i64_i32 v[82:83], s[2:3], v84, s7, v[82:83]
	v_lshl_add_u64 v[82:83], v[152:153], 1, v[82:83]
	s_and_b64 vcc, exec, s[40:41]
	v_cvt_pk_bf16_f32 v78, v78, v79
	v_cvt_pk_bf16_f32 v79, v80, v81
	v_cvt_pk_bf16_f32 v80, v74, v75
	v_cvt_pk_bf16_f32 v81, v76, v77
	s_bitcmp1_b32 s100, 0
	s_cselect_b64 exec, -1, 0
	flat_store_dwordx4 v[82:83], v[78:81]
	s_mov_b64 exec, -1
	s_cbranch_vccnz .LBB0_437
	v_mul_f32_e32 v70, 0xbfb8aa3b, v70
	v_mul_f32_e32 v66, 0xbfb8aa3b, v66
	v_mul_f32_e32 v71, 0xbfb8aa3b, v71
	v_mul_f32_e32 v67, 0xbfb8aa3b, v67
	v_mul_f32_e32 v72, 0xbfb8aa3b, v72
	v_mul_f32_e32 v68, 0xbfb8aa3b, v68
	v_mul_f32_e32 v73, 0xbfb8aa3b, v73
	v_mul_f32_e32 v69, 0xbfb8aa3b, v69
	v_exp_f32_e32 v70, v70
	v_exp_f32_e32 v66, v66
	v_exp_f32_e32 v71, v71
	v_exp_f32_e32 v67, v67
	v_exp_f32_e32 v72, v72
	v_exp_f32_e32 v68, v68
	v_exp_f32_e32 v73, v73
	v_exp_f32_e32 v69, v69
	v_add_f32_e32 v70, 1.0, v70
	v_add_f32_e32 v66, 1.0, v66
	v_add_f32_e32 v71, 1.0, v71
	v_add_f32_e32 v67, 1.0, v67
	v_add_f32_e32 v72, 1.0, v72
	v_add_f32_e32 v68, 1.0, v68
	v_add_f32_e32 v73, 1.0, v73
	v_add_f32_e32 v69, 1.0, v69
	v_rcp_f32_e32 v70, v70
	v_rcp_f32_e32 v66, v66
	v_rcp_f32_e32 v71, v71
	v_rcp_f32_e32 v67, v67
	v_rcp_f32_e32 v72, v72
	v_rcp_f32_e32 v68, v68
	v_rcp_f32_e32 v73, v73
	v_rcp_f32_e32 v69, v69
.LBB0_437:
	s_and_b64 vcc, exec, s[40:41]
	v_cvt_pk_bf16_f32 v70, v70, v71
	v_cvt_pk_bf16_f32 v71, v72, v73
	v_cvt_pk_bf16_f32 v72, v66, v67
	v_cvt_pk_bf16_f32 v73, v68, v69
	s_bitcmp1_b32 s100, 1
	s_cselect_b64 exec, -1, 0
	flat_store_dwordx4 v[82:83], v[70:73] offset:256
	s_mov_b64 exec, -1
	s_cbranch_vccnz .LBB0_439
	v_mul_f32_e32 v62, 0xbfb8aa3b, v62
	v_mul_f32_e32 v58, 0xbfb8aa3b, v58
	v_mul_f32_e32 v63, 0xbfb8aa3b, v63
	v_mul_f32_e32 v59, 0xbfb8aa3b, v59
	v_mul_f32_e32 v64, 0xbfb8aa3b, v64
	v_mul_f32_e32 v60, 0xbfb8aa3b, v60
	v_mul_f32_e32 v65, 0xbfb8aa3b, v65
	v_mul_f32_e32 v61, 0xbfb8aa3b, v61
	v_exp_f32_e32 v62, v62
	v_exp_f32_e32 v58, v58
	v_exp_f32_e32 v63, v63
	v_exp_f32_e32 v59, v59
	v_exp_f32_e32 v64, v64
	v_exp_f32_e32 v60, v60
	v_exp_f32_e32 v65, v65
	v_exp_f32_e32 v61, v61
	v_add_f32_e32 v62, 1.0, v62
	v_add_f32_e32 v58, 1.0, v58
	v_add_f32_e32 v63, 1.0, v63
	v_add_f32_e32 v59, 1.0, v59
	v_add_f32_e32 v64, 1.0, v64
	v_add_f32_e32 v60, 1.0, v60
	v_add_f32_e32 v65, 1.0, v65
	v_add_f32_e32 v61, 1.0, v61
	v_rcp_f32_e32 v62, v62
	v_rcp_f32_e32 v58, v58
	v_rcp_f32_e32 v63, v63
	v_rcp_f32_e32 v59, v59
	v_rcp_f32_e32 v64, v64
	v_rcp_f32_e32 v60, v60
	v_rcp_f32_e32 v65, v65
	v_rcp_f32_e32 v61, v61
; __device__ __forceinline__ unsigned cvt_pk_bf16(float lo, float hi) { unsigned r; asm volatile("v_cvt_pk_bf16_f32 %0, %1, %2" : "=v"(r) : "v"(lo), "v"(hi)); return r; }
; __device__ __forceinline__ float fsig(float x) { return __builtin_amdgcn_rcpf(1.0f + __expf(-x)); }
;     __device__ __forceinline__ void operator()(const f32x4 (&acc)[2][2][4][2], const Unit& u, int wr, int wc, int fr, int fq) const {
;     ...
;             for (int m = 0; m < 4; ++m) { bf16_t* rowp = O + (size_t)(row0 + ai * HALF + m * 16) * LDP + col0;
; #pragma unroll
;                 for (int bj = 0; bj < 2; ++bj) { f32x4 v0 = acc[ai][bj][m][0], v1 = acc[ai][bj][m][1];
;                     if (act == 1) {
; #pragma unroll
;                         for (int j = 0; j < 4; ++j) { v0[j] = v0[j] * fsig(v0[j]); v1[j] = v1[j] * fsig(v1[j]); } }
;                     else if (act == 2) {
; #pragma unroll
;                         for (int j = 0; j < 4; ++j) { v0[j] = fsig(v0[j]); v1[j] = fsig(v1[j]); } }
;                     u32x4 w; w.x = cvt_pk_bf16(v0[0], v0[1]); w.y = cvt_pk_bf16(v0[2], v0[3]); w.z = cvt_pk_bf16(v1[0], v1[1]); w.w = cvt_pk_bf16(v1[2], v1[3]);
;                     *(u32x4*)(rowp + bj * HALF) = w; } }
.LBB0_439:
	v_add_u32_e32 v68, 0x80, v159
	v_mov_b64_e32 v[66:67], s[42:43]
	v_mad_i64_i32 v[66:67], s[2:3], v68, s7, v[66:67]
	v_lshl_add_u64 v[66:67], v[152:153], 1, v[66:67]
	s_and_b64 vcc, exec, s[40:41]
	v_cvt_pk_bf16_f32 v62, v62, v63
	v_cvt_pk_bf16_f32 v63, v64, v65
	v_cvt_pk_bf16_f32 v64, v58, v59
	v_cvt_pk_bf16_f32 v65, v60, v61
	s_bitcmp1_b32 s100, 2
	s_cselect_b64 exec, -1, 0
	flat_store_dwordx4 v[66:67], v[62:65]
	s_mov_b64 exec, -1
	s_cbranch_vccnz .LBB0_441
	v_mul_f32_e32 v54, 0xbfb8aa3b, v54
	v_mul_f32_e32 v50, 0xbfb8aa3b, v50
	v_mul_f32_e32 v55, 0xbfb8aa3b, v55
	v_mul_f32_e32 v51, 0xbfb8aa3b, v51
	v_mul_f32_e32 v56, 0xbfb8aa3b, v56
	v_mul_f32_e32 v52, 0xbfb8aa3b, v52
	v_mul_f32_e32 v57, 0xbfb8aa3b, v57
	v_mul_f32_e32 v53, 0xbfb8aa3b, v53
	v_exp_f32_e32 v54, v54
	v_exp_f32_e32 v50, v50
	v_exp_f32_e32 v55, v55
	v_exp_f32_e32 v51, v51
	v_exp_f32_e32 v56, v56
	v_exp_f32_e32 v52, v52
	v_exp_f32_e32 v57, v57
	v_exp_f32_e32 v53, v53
	v_add_f32_e32 v54, 1.0, v54
	v_add_f32_e32 v50, 1.0, v50
	v_add_f32_e32 v55, 1.0, v55
	v_add_f32_e32 v51, 1.0, v51
	v_add_f32_e32 v56, 1.0, v56
	v_add_f32_e32 v52, 1.0, v52
	v_add_f32_e32 v57, 1.0, v57
	v_add_f32_e32 v53, 1.0, v53
	v_rcp_f32_e32 v54, v54
	v_rcp_f32_e32 v50, v50
	v_rcp_f32_e32 v55, v55
	v_rcp_f32_e32 v51, v51
	v_rcp_f32_e32 v56, v56
	v_rcp_f32_e32 v52, v52
	v_rcp_f32_e32 v57, v57
	v_rcp_f32_e32 v53, v53
.LBB0_441:
	s_and_b64 vcc, exec, s[40:41]
	v_cvt_pk_bf16_f32 v54, v54, v55
	v_cvt_pk_bf16_f32 v55, v56, v57
	v_cvt_pk_bf16_f32 v56, v50, v51
	v_cvt_pk_bf16_f32 v57, v52, v53
	s_bitcmp1_b32 s100, 3
	s_cselect_b64 exec, -1, 0
	flat_store_dwordx4 v[66:67], v[54:57] offset:256
	s_mov_b64 exec, -1
	s_cbranch_vccnz .LBB0_443
	v_mul_f32_e32 v46, 0xbfb8aa3b, v46
	v_mul_f32_e32 v42, 0xbfb8aa3b, v42
	v_mul_f32_e32 v47, 0xbfb8aa3b, v47
	v_mul_f32_e32 v43, 0xbfb8aa3b, v43
	v_mul_f32_e32 v48, 0xbfb8aa3b, v48
	v_mul_f32_e32 v44, 0xbfb8aa3b, v44
	v_mul_f32_e32 v49, 0xbfb8aa3b, v49
	v_mul_f32_e32 v45, 0xbfb8aa3b, v45
	v_exp_f32_e32 v46, v46
	v_exp_f32_e32 v42, v42
	v_exp_f32_e32 v47, v47
	v_exp_f32_e32 v43, v43
	v_exp_f32_e32 v48, v48
	v_exp_f32_e32 v44, v44
	v_exp_f32_e32 v49, v49
	v_exp_f32_e32 v45, v45
	v_add_f32_e32 v46, 1.0, v46
	v_add_f32_e32 v42, 1.0, v42
	v_add_f32_e32 v47, 1.0, v47
	v_add_f32_e32 v43, 1.0, v43
	v_add_f32_e32 v48, 1.0, v48
	v_add_f32_e32 v44, 1.0, v44
	v_add_f32_e32 v49, 1.0, v49
	v_add_f32_e32 v45, 1.0, v45
	v_rcp_f32_e32 v46, v46
	v_rcp_f32_e32 v42, v42
	v_rcp_f32_e32 v47, v47
	v_rcp_f32_e32 v43, v43
	v_rcp_f32_e32 v48, v48
	v_rcp_f32_e32 v44, v44
	v_rcp_f32_e32 v49, v49
	v_rcp_f32_e32 v45, v45
.LBB0_443:
	v_add_u32_e32 v52, 0x90, v159
	v_mov_b64_e32 v[50:51], s[42:43]
	v_mad_i64_i32 v[50:51], s[2:3], v52, s7, v[50:51]
	v_lshl_add_u64 v[50:51], v[152:153], 1, v[50:51]
	s_and_b64 vcc, exec, s[40:41]
	v_cvt_pk_bf16_f32 v46, v46, v47
	v_cvt_pk_bf16_f32 v47, v48, v49
	v_cvt_pk_bf16_f32 v48, v42, v43
	v_cvt_pk_bf16_f32 v49, v44, v45
	s_bitcmp1_b32 s100, 2
	s_cselect_b64 exec, -1, 0
	flat_store_dwordx4 v[50:51], v[46:49]
	s_mov_b64 exec, -1
	s_cbranch_vccnz .LBB0_445
	v_mul_f32_e32 v38, 0xbfb8aa3b, v38
	v_mul_f32_e32 v34, 0xbfb8aa3b, v34
	v_mul_f32_e32 v39, 0xbfb8aa3b, v39
	v_mul_f32_e32 v35, 0xbfb8aa3b, v35
	v_mul_f32_e32 v40, 0xbfb8aa3b, v40
	v_mul_f32_e32 v36, 0xbfb8aa3b, v36
	v_mul_f32_e32 v41, 0xbfb8aa3b, v41
	v_mul_f32_e32 v37, 0xbfb8aa3b, v37
	v_exp_f32_e32 v38, v38
	v_exp_f32_e32 v34, v34
	v_exp_f32_e32 v39, v39
	v_exp_f32_e32 v35, v35
	v_exp_f32_e32 v40, v40
	v_exp_f32_e32 v36, v36
	v_exp_f32_e32 v41, v41
	v_exp_f32_e32 v37, v37
	v_add_f32_e32 v38, 1.0, v38
	v_add_f32_e32 v34, 1.0, v34
	v_add_f32_e32 v39, 1.0, v39
	v_add_f32_e32 v35, 1.0, v35
	v_add_f32_e32 v40, 1.0, v40
	v_add_f32_e32 v36, 1.0, v36
	v_add_f32_e32 v41, 1.0, v41
	v_add_f32_e32 v37, 1.0, v37
	v_rcp_f32_e32 v38, v38
	v_rcp_f32_e32 v34, v34
	v_rcp_f32_e32 v39, v39
	v_rcp_f32_e32 v35, v35
	v_rcp_f32_e32 v40, v40
	v_rcp_f32_e32 v36, v36
	v_rcp_f32_e32 v41, v41
	v_rcp_f32_e32 v37, v37
.LBB0_445:
	s_and_b64 vcc, exec, s[40:41]
	v_cvt_pk_bf16_f32 v38, v38, v39
	v_cvt_pk_bf16_f32 v39, v40, v41
	v_cvt_pk_bf16_f32 v40, v34, v35
	v_cvt_pk_bf16_f32 v41, v36, v37
	s_bitcmp1_b32 s100, 3
	s_cselect_b64 exec, -1, 0
	flat_store_dwordx4 v[50:51], v[38:41] offset:256
	s_mov_b64 exec, -1
	s_cbranch_vccnz .LBB0_447
	v_mul_f32_e32 v30, 0xbfb8aa3b, v30
	v_mul_f32_e32 v26, 0xbfb8aa3b, v26
	v_mul_f32_e32 v31, 0xbfb8aa3b, v31
	v_mul_f32_e32 v27, 0xbfb8aa3b, v27
	v_mul_f32_e32 v32, 0xbfb8aa3b, v32
	v_mul_f32_e32 v28, 0xbfb8aa3b, v28
	v_mul_f32_e32 v33, 0xbfb8aa3b, v33
	v_mul_f32_e32 v29, 0xbfb8aa3b, v29
	v_exp_f32_e32 v30, v30
	v_exp_f32_e32 v26, v26
	v_exp_f32_e32 v31, v31
	v_exp_f32_e32 v27, v27
	v_exp_f32_e32 v32, v32
	v_exp_f32_e32 v28, v28
	v_exp_f32_e32 v33, v33
	v_exp_f32_e32 v29, v29
	v_add_f32_e32 v30, 1.0, v30
	v_add_f32_e32 v26, 1.0, v26
	v_add_f32_e32 v31, 1.0, v31
	v_add_f32_e32 v27, 1.0, v27
	v_add_f32_e32 v32, 1.0, v32
	v_add_f32_e32 v28, 1.0, v28
	v_add_f32_e32 v33, 1.0, v33
	v_add_f32_e32 v29, 1.0, v29
	v_rcp_f32_e32 v30, v30
	v_rcp_f32_e32 v26, v26
	v_rcp_f32_e32 v31, v31
	v_rcp_f32_e32 v27, v27
	v_rcp_f32_e32 v32, v32
	v_rcp_f32_e32 v28, v28
	v_rcp_f32_e32 v33, v33
	v_rcp_f32_e32 v29, v29
; __device__ __forceinline__ unsigned cvt_pk_bf16(float lo, float hi) { unsigned r; asm volatile("v_cvt_pk_bf16_f32 %0, %1, %2" : "=v"(r) : "v"(lo), "v"(hi)); return r; }
; __device__ __forceinline__ float fsig(float x) { return __builtin_amdgcn_rcpf(1.0f + __expf(-x)); }
;     __device__ __forceinline__ void operator()(const f32x4 (&acc)[2][2][4][2], const Unit& u, int wr, int wc, int fr, int fq) const {
;     ...
;             for (int m = 0; m < 4; ++m) { bf16_t* rowp = O + (size_t)(row0 + ai * HALF + m * 16) * LDP + col0;
; #pragma unroll
;                 for (int bj = 0; bj < 2; ++bj) { f32x4 v0 = acc[ai][bj][m][0], v1 = acc[ai][bj][m][1];
;                     if (act == 1) {
; #pragma unroll
;                         for (int j = 0; j < 4; ++j) { v0[j] = v0[j] * fsig(v0[j]); v1[j] = v1[j] * fsig(v1[j]); } }
;                     else if (act == 2) {
; #pragma unroll
;                         for (int j = 0; j < 4; ++j) { v0[j] = fsig(v0[j]); v1[j] = fsig(v1[j]); } }
;                     u32x4 w; w.x = cvt_pk_bf16(v0[0], v0[1]); w.y = cvt_pk_bf16(v0[2], v0[3]); w.z = cvt_pk_bf16(v1[0], v1[1]); w.w = cvt_pk_bf16(v1[2], v1[3]);
;                     *(u32x4*)(rowp + bj * HALF) = w; } }
.LBB0_447:
	v_add_u32_e32 v36, 0xa0, v159
	v_mov_b64_e32 v[34:35], s[42:43]
	v_mad_i64_i32 v[34:35], s[2:3], v36, s7, v[34:35]
	v_lshl_add_u64 v[34:35], v[152:153], 1, v[34:35]
	s_and_b64 vcc, exec, s[40:41]
	v_cvt_pk_bf16_f32 v30, v30, v31
	v_cvt_pk_bf16_f32 v31, v32, v33
	v_cvt_pk_bf16_f32 v32, v26, v27
	v_cvt_pk_bf16_f32 v33, v28, v29
	s_bitcmp1_b32 s100, 2
	s_cselect_b64 exec, -1, 0
	flat_store_dwordx4 v[34:35], v[30:33]
	s_mov_b64 exec, -1
	s_cbranch_vccnz .LBB0_449
	v_mul_f32_e32 v22, 0xbfb8aa3b, v22
	v_mul_f32_e32 v18, 0xbfb8aa3b, v18
	v_mul_f32_e32 v23, 0xbfb8aa3b, v23
	v_mul_f32_e32 v19, 0xbfb8aa3b, v19
	v_mul_f32_e32 v24, 0xbfb8aa3b, v24
	v_mul_f32_e32 v20, 0xbfb8aa3b, v20
	v_mul_f32_e32 v25, 0xbfb8aa3b, v25
	v_mul_f32_e32 v21, 0xbfb8aa3b, v21
	v_exp_f32_e32 v22, v22
	v_exp_f32_e32 v18, v18
	v_exp_f32_e32 v23, v23
	v_exp_f32_e32 v19, v19
	v_exp_f32_e32 v24, v24
	v_exp_f32_e32 v20, v20
	v_exp_f32_e32 v25, v25
	v_exp_f32_e32 v21, v21
	v_add_f32_e32 v22, 1.0, v22
	v_add_f32_e32 v18, 1.0, v18
	v_add_f32_e32 v23, 1.0, v23
	v_add_f32_e32 v19, 1.0, v19
	v_add_f32_e32 v24, 1.0, v24
	v_add_f32_e32 v20, 1.0, v20
	v_add_f32_e32 v25, 1.0, v25
	v_add_f32_e32 v21, 1.0, v21
	v_rcp_f32_e32 v22, v22
	v_rcp_f32_e32 v18, v18
	v_rcp_f32_e32 v23, v23
	v_rcp_f32_e32 v19, v19
	v_rcp_f32_e32 v24, v24
	v_rcp_f32_e32 v20, v20
	v_rcp_f32_e32 v25, v25
	v_rcp_f32_e32 v21, v21
.LBB0_449:
	s_and_b64 vcc, exec, s[40:41]
	v_cvt_pk_bf16_f32 v22, v22, v23
	v_cvt_pk_bf16_f32 v23, v24, v25
	v_cvt_pk_bf16_f32 v24, v18, v19
	v_cvt_pk_bf16_f32 v25, v20, v21
	s_bitcmp1_b32 s100, 3
	s_cselect_b64 exec, -1, 0
	flat_store_dwordx4 v[34:35], v[22:25] offset:256
	s_mov_b64 exec, -1
	s_cbranch_vccnz .LBB0_451
	v_mul_f32_e32 v14, 0xbfb8aa3b, v14
	v_mul_f32_e32 v10, 0xbfb8aa3b, v10
	v_mul_f32_e32 v15, 0xbfb8aa3b, v15
	v_mul_f32_e32 v11, 0xbfb8aa3b, v11
	v_mul_f32_e32 v16, 0xbfb8aa3b, v16
	v_mul_f32_e32 v12, 0xbfb8aa3b, v12
	v_mul_f32_e32 v17, 0xbfb8aa3b, v17
	v_mul_f32_e32 v13, 0xbfb8aa3b, v13
	v_exp_f32_e32 v14, v14
	v_exp_f32_e32 v10, v10
	v_exp_f32_e32 v15, v15
	v_exp_f32_e32 v11, v11
	v_exp_f32_e32 v16, v16
	v_exp_f32_e32 v12, v12
	v_exp_f32_e32 v17, v17
	v_exp_f32_e32 v13, v13
	v_add_f32_e32 v14, 1.0, v14
	v_add_f32_e32 v10, 1.0, v10
	v_add_f32_e32 v15, 1.0, v15
	v_add_f32_e32 v11, 1.0, v11
	v_add_f32_e32 v16, 1.0, v16
	v_add_f32_e32 v12, 1.0, v12
	v_add_f32_e32 v17, 1.0, v17
	v_add_f32_e32 v13, 1.0, v13
	v_rcp_f32_e32 v14, v14
	v_rcp_f32_e32 v10, v10
	v_rcp_f32_e32 v15, v15
	v_rcp_f32_e32 v11, v11
	v_rcp_f32_e32 v16, v16
	v_rcp_f32_e32 v12, v12
	v_rcp_f32_e32 v17, v17
	v_rcp_f32_e32 v13, v13
.LBB0_451:
	v_add_u32_e32 v20, 0xb0, v159
	v_mov_b64_e32 v[18:19], s[42:43]
	v_mad_i64_i32 v[18:19], s[2:3], v20, s7, v[18:19]
	v_lshl_add_u64 v[18:19], v[152:153], 1, v[18:19]
	s_and_b64 vcc, exec, s[40:41]
	v_cvt_pk_bf16_f32 v14, v14, v15
	v_cvt_pk_bf16_f32 v15, v16, v17
	v_cvt_pk_bf16_f32 v16, v10, v11
	v_cvt_pk_bf16_f32 v17, v12, v13
	s_bitcmp1_b32 s100, 2
	s_cselect_b64 exec, -1, 0
	flat_store_dwordx4 v[18:19], v[14:17]
	s_mov_b64 exec, -1
	s_cbranch_vccnz .LBB0_453
	v_mul_f32_e32 v6, 0xbfb8aa3b, v6
	v_mul_f32_e32 v2, 0xbfb8aa3b, v2
	v_mul_f32_e32 v7, 0xbfb8aa3b, v7
	v_mul_f32_e32 v3, 0xbfb8aa3b, v3
	v_mul_f32_e32 v8, 0xbfb8aa3b, v8
	v_mul_f32_e32 v4, 0xbfb8aa3b, v4
	v_mul_f32_e32 v9, 0xbfb8aa3b, v9
	v_mul_f32_e32 v5, 0xbfb8aa3b, v5
	v_exp_f32_e32 v6, v6
	v_exp_f32_e32 v2, v2
	v_exp_f32_e32 v7, v7
	v_exp_f32_e32 v3, v3
	v_exp_f32_e32 v8, v8
	v_exp_f32_e32 v4, v4
	v_exp_f32_e32 v9, v9
	v_exp_f32_e32 v5, v5
	v_add_f32_e32 v6, 1.0, v6
	v_add_f32_e32 v2, 1.0, v2
	v_add_f32_e32 v7, 1.0, v7
	v_add_f32_e32 v3, 1.0, v3
	v_add_f32_e32 v8, 1.0, v8
	v_add_f32_e32 v4, 1.0, v4
	v_add_f32_e32 v9, 1.0, v9
	v_add_f32_e32 v5, 1.0, v5
	v_rcp_f32_e32 v6, v6
	v_rcp_f32_e32 v2, v2
	v_rcp_f32_e32 v7, v7
	v_rcp_f32_e32 v3, v3
	v_rcp_f32_e32 v8, v8
	v_rcp_f32_e32 v4, v4
	v_rcp_f32_e32 v9, v9
	v_rcp_f32_e32 v5, v5
.LBB0_453:
	s_andn2_b64 vcc, exec, s[38:39]
	s_mov_b64 s[2:3], -1
	v_cvt_pk_bf16_f32 v6, v6, v7
	v_cvt_pk_bf16_f32 v7, v8, v9
	v_cvt_pk_bf16_f32 v8, v2, v3
	v_cvt_pk_bf16_f32 v9, v4, v5
	s_bitcmp1_b32 s100, 3
	s_cselect_b64 exec, -1, 0
	flat_store_dwordx4 v[18:19], v[6:9] offset:256
	s_mov_b64 exec, -1
	s_cbranch_vccnz .LBB0_414
	s_andn2_b64 vcc, exec, s[0:1]
	s_cbranch_vccnz .LBB0_413
	s_barrier
	s_branch .LBB0_413

; #define PG8_STAGE(bufoff, gbase, voff) do { _Pragma("unroll") for (int _i = 0; _i < 2; ++_i) \
;         __builtin_amdgcn_global_load_lds((const unsigned*)((const char*)(gbase) + (voff)[_i]), (PG8_LAS unsigned*)(lds + (bufoff) + ldsw + _i * 8192), 16, 0, 0); } while (0)
; #define PG8_LDA(dst, b, h) do { _Pragma("unroll") for (int m = 0; m < 4; ++m) _Pragma("unroll") for (int k = 0; k < 2; ++k) dst[m][k] = *(const PG8_LAS bf16x8*)(lds + PG8_SA(b, h) + aoff + m * 2048 + k * 1024); } while (0)
; #define PG8_LDB(dst, b, h) do { _Pragma("unroll") for (int n = 0; n < 2; ++n) _Pragma("unroll") for (int k = 0; k < 2; ++k) dst[n][k] = *(const PG8_LAS bf16x8*)(lds + PG8_SB(b, h) + boff + n * 2048 + k * 1024); } while (0)
; #define PG8_MMA(ai, bj, At, Bt) do { __builtin_amdgcn_s_setprio(1); _Pragma("unroll") for (int m = 0; m < 4; ++m) _Pragma("unroll") for (int n = 0; n < 2; ++n) _Pragma("unroll") for (int k = 0; k < 2; ++k) \
;         acc[ai][bj][m][n] = __builtin_amdgcn_mfma_f32_16x16x32_bf16(Bt[n][k], At[m][k], acc[ai][bj][m][n], 0, 0, 0); __builtin_amdgcn_s_setprio(0); } while (0)
; #define PG8_WAIT_V(n) asm volatile("s_waitcnt vmcnt(" #n ")" ::: "memory")
; #define PG8_WAIT_L(n) asm volatile("s_waitcnt lgkmcnt(" #n ")" ::: "memory")
; #define PG8_BAR __builtin_amdgcn_s_barrier()
; template <class Epi, class Sched, bool ALIGN_EPI = false, bool SP2 = false>
; __device__ __forceinline__ void gemm_phase(PG8_LAS unsigned char* lds, const Gemm g, const Sched& S, const Epi& E) {
;     ...
;             PG8_WAIT_V(8); PG8_WAIT_L(0); PG8_BAR; PG8_MMA(0, 0, At, B0); PG8_MMA(0, 1, At, B1); PG8_BAR; PG8_SCHED;
;             PG8_LDA(At, 0, 1); PG8_STAGE(PG8_SB(0, 0), b2, voffB); PG8_STAGE(PG8_SB(0, 1), b2 + hstep, voffB); PG8_STAGE(PG8_SA(0, 0), a2, voffA);
;             PG8_WAIT_V(8); PG8_WAIT_L(0); PG8_BAR; PG8_MMA(1, 0, At, B0); PG8_MMA(1, 1, At, B1); PG8_BAR; PG8_SCHED;
;             PG8_LDB(B0, 1, 0); PG8_LDB(B1, 1, 1); PG8_SCHED; PG8_LDA(At, 1, 0); PG8_STAGE(PG8_SA(0, 1), a2 + hstep, voffA);
;             PG8_WAIT_V(8); PG8_WAIT_L(0); PG8_BAR; PG8_MMA(0, 0, At, B0); PG8_MMA(0, 1, At, B1); PG8_BAR; PG8_SCHED;
;             PG8_LDA(At, 1, 1); PG8_STAGE(PG8_SB(1, 0), b3, voffB); PG8_STAGE(PG8_SB(1, 1), b3 + hstep, voffB); PG8_STAGE(PG8_SA(1, 0), a3, voffA);
;             PG8_WAIT_V(8); PG8_WAIT_L(0); PG8_BAR; PG8_MMA(1, 0, At, B0); PG8_MMA(1, 1, At, B1); PG8_BAR; PG8_SCHED;
.Lg1q_sp0:
	s_barrier
	s_setprio 1
	s_waitcnt lgkmcnt(0)
	s_bitcmp1_b32 s100, 0
	s_cbranch_scc0 .Lg1q_sp0_b
	v_mfma_f32_16x16x32_bf16 v[126:129], v[152:155], v[202:205], v[126:129]
	v_mfma_f32_16x16x32_bf16 v[122:125], v[164:167], v[202:205], v[122:125]
	v_mfma_f32_16x16x32_bf16 v[110:113], v[152:155], v[214:217], v[110:113]
	v_mfma_f32_16x16x32_bf16 v[106:109], v[164:167], v[214:217], v[106:109]
	v_mfma_f32_16x16x32_bf16 v[94:97], v[152:155], v[222:225], v[94:97]
	v_mfma_f32_16x16x32_bf16 v[90:93], v[164:167], v[222:225], v[90:93]
	v_mfma_f32_16x16x32_bf16 v[78:81], v[152:155], v[230:233], v[78:81]
	v_mfma_f32_16x16x32_bf16 v[74:77], v[164:167], v[230:233], v[74:77]
	v_mfma_f32_16x16x32_bf16 v[126:129], v[160:163], v[206:209], v[126:129]
	v_mfma_f32_16x16x32_bf16 v[122:125], v[182:185], v[206:209], v[122:125]
	v_mfma_f32_16x16x32_bf16 v[110:113], v[160:163], v[218:221], v[110:113]
	v_mfma_f32_16x16x32_bf16 v[106:109], v[182:185], v[218:221], v[106:109]
	v_mfma_f32_16x16x32_bf16 v[94:97], v[160:163], v[226:229], v[94:97]
	v_mfma_f32_16x16x32_bf16 v[90:93], v[182:185], v[226:229], v[90:93]
	v_mfma_f32_16x16x32_bf16 v[78:81], v[160:163], v[234:237], v[78:81]
	v_mfma_f32_16x16x32_bf16 v[74:77], v[182:185], v[234:237], v[74:77]
.Lg1q_sp0_b:
	s_bitcmp1_b32 s100, 1
	s_cbranch_scc0 .Lg1q_sp0_e
	v_mfma_f32_16x16x32_bf16 v[118:121], v[186:189], v[202:205], v[118:121]
	v_mfma_f32_16x16x32_bf16 v[114:117], v[194:197], v[202:205], v[114:117]
	v_mfma_f32_16x16x32_bf16 v[102:105], v[186:189], v[214:217], v[102:105]
	v_mfma_f32_16x16x32_bf16 v[98:101], v[194:197], v[214:217], v[98:101]
	v_mfma_f32_16x16x32_bf16 v[86:89], v[186:189], v[222:225], v[86:89]
	v_mfma_f32_16x16x32_bf16 v[82:85], v[194:197], v[222:225], v[82:85]
	v_mfma_f32_16x16x32_bf16 v[70:73], v[186:189], v[230:233], v[70:73]
	v_mfma_f32_16x16x32_bf16 v[66:69], v[194:197], v[230:233], v[66:69]
	v_mfma_f32_16x16x32_bf16 v[118:121], v[190:193], v[206:209], v[118:121]
	v_mfma_f32_16x16x32_bf16 v[114:117], v[198:201], v[206:209], v[114:117]
	v_mfma_f32_16x16x32_bf16 v[102:105], v[190:193], v[218:221], v[102:105]
	v_mfma_f32_16x16x32_bf16 v[98:101], v[198:201], v[218:221], v[98:101]
	v_mfma_f32_16x16x32_bf16 v[86:89], v[190:193], v[226:229], v[86:89]
	v_mfma_f32_16x16x32_bf16 v[82:85], v[198:201], v[226:229], v[82:85]
	v_mfma_f32_16x16x32_bf16 v[70:73], v[190:193], v[234:237], v[70:73]
	v_mfma_f32_16x16x32_bf16 v[66:69], v[198:201], v[234:237], v[66:69]
.Lg1q_sp0_e:
	s_setprio 0
	s_branch .Lg1q_join0
.Lg1q_sp1:
	s_barrier
	s_setprio 1
	s_waitcnt lgkmcnt(0)
	s_bitcmp1_b32 s100, 2
	s_cbranch_scc0 .Lg1q_sp1_b
	v_mfma_f32_16x16x32_bf16 v[62:65], v[152:155], v[202:205], v[62:65]
	v_mfma_f32_16x16x32_bf16 v[58:61], v[164:167], v[202:205], v[58:61]
	v_mfma_f32_16x16x32_bf16 v[46:49], v[152:155], v[214:217], v[46:49]
	v_mfma_f32_16x16x32_bf16 v[42:45], v[164:167], v[214:217], v[42:45]
	v_mfma_f32_16x16x32_bf16 v[30:33], v[152:155], v[222:225], v[30:33]
	v_mfma_f32_16x16x32_bf16 v[26:29], v[164:167], v[222:225], v[26:29]
	v_mfma_f32_16x16x32_bf16 v[14:17], v[152:155], v[230:233], v[14:17]
	v_mfma_f32_16x16x32_bf16 v[10:13], v[164:167], v[230:233], v[10:13]
	v_mfma_f32_16x16x32_bf16 v[62:65], v[160:163], v[206:209], v[62:65]
	v_mfma_f32_16x16x32_bf16 v[58:61], v[182:185], v[206:209], v[58:61]
	v_mfma_f32_16x16x32_bf16 v[46:49], v[160:163], v[218:221], v[46:49]
	v_mfma_f32_16x16x32_bf16 v[42:45], v[182:185], v[218:221], v[42:45]
	v_mfma_f32_16x16x32_bf16 v[30:33], v[160:163], v[226:229], v[30:33]
	v_mfma_f32_16x16x32_bf16 v[26:29], v[182:185], v[226:229], v[26:29]
	v_mfma_f32_16x16x32_bf16 v[14:17], v[160:163], v[234:237], v[14:17]
	v_mfma_f32_16x16x32_bf16 v[10:13], v[182:185], v[234:237], v[10:13]
.Lg1q_sp1_b:
	s_bitcmp1_b32 s100, 3
	s_cbranch_scc0 .Lg1q_sp1_e
	v_mfma_f32_16x16x32_bf16 v[54:57], v[186:189], v[202:205], v[54:57]
	v_mfma_f32_16x16x32_bf16 v[50:53], v[194:197], v[202:205], v[50:53]
	v_mfma_f32_16x16x32_bf16 v[38:41], v[186:189], v[214:217], v[38:41]
	v_mfma_f32_16x16x32_bf16 v[34:37], v[194:197], v[214:217], v[34:37]
	v_mfma_f32_16x16x32_bf16 v[22:25], v[186:189], v[222:225], v[22:25]
	v_mfma_f32_16x16x32_bf16 v[18:21], v[194:197], v[222:225], v[18:21]
	v_mfma_f32_16x16x32_bf16 v[6:9], v[186:189], v[230:233], v[6:9]
	v_mfma_f32_16x16x32_bf16 v[2:5], v[194:197], v[230:233], v[2:5]
	v_mfma_f32_16x16x32_bf16 v[54:57], v[190:193], v[206:209], v[54:57]
	v_mfma_f32_16x16x32_bf16 v[50:53], v[198:201], v[206:209], v[50:53]
	v_mfma_f32_16x16x32_bf16 v[38:41], v[190:193], v[218:221], v[38:41]
	v_mfma_f32_16x16x32_bf16 v[34:37], v[198:201], v[218:221], v[34:37]
	v_mfma_f32_16x16x32_bf16 v[22:25], v[190:193], v[226:229], v[22:25]
	v_mfma_f32_16x16x32_bf16 v[18:21], v[198:201], v[226:229], v[18:21]
	v_mfma_f32_16x16x32_bf16 v[6:9], v[190:193], v[234:237], v[6:9]
	v_mfma_f32_16x16x32_bf16 v[2:5], v[198:201], v[234:237], v[2:5]

; __global__ void __launch_bounds__(NTHR, 2) mega_fwd(Args args) {
	.amdhsa_kernel _Z8mega_fwd4Args
		.amdhsa_group_segment_fixed_size 0
		.amdhsa_private_segment_fixed_size 0
		.amdhsa_kernarg_size 448
		.amdhsa_user_sgpr_count 2
		.amdhsa_user_sgpr_dispatch_ptr 0
		.amdhsa_user_sgpr_queue_ptr 0
		.amdhsa_user_sgpr_kernarg_segment_ptr 1
		.amdhsa_user_sgpr_dispatch_id 0
		.amdhsa_user_sgpr_kernarg_preload_length 0
		.amdhsa_user_sgpr_kernarg_preload_offset 0
		.amdhsa_user_sgpr_private_segment_size 0
		.amdhsa_uses_dynamic_stack 0
		.amdhsa_enable_private_segment 0
		.amdhsa_system_sgpr_workgroup_id_x 1
		.amdhsa_system_sgpr_workgroup_id_y 0
		.amdhsa_system_sgpr_workgroup_id_z 0
		.amdhsa_system_sgpr_workgroup_info 0
		.amdhsa_system_vgpr_workitem_id 2
		.amdhsa_next_free_vgpr 255
		.amdhsa_next_free_sgpr 102
		.amdhsa_accum_offset 256
		.amdhsa_reserve_vcc 1
		.amdhsa_float_round_mode_32 0
		.amdhsa_float_round_mode_16_64 0
		.amdhsa_float_denorm_mode_32 3
		.amdhsa_float_denorm_mode_16_64 3
		.amdhsa_dx10_clamp 1
		.amdhsa_ieee_mode 1
		.amdhsa_fp16_overflow 0
		.amdhsa_tg_split 0
		.amdhsa_exception_fp_ieee_invalid_op 0
		.amdhsa_exception_fp_denorm_src 0
		.amdhsa_exception_fp_ieee_div_zero 0
		.amdhsa_exception_fp_ieee_overflow 0
		.amdhsa_exception_fp_ieee_underflow 0
		.amdhsa_exception_fp_ieee_inexact 0
		.amdhsa_exception_int_div_zero 0
	.end_amdhsa_kernel

; __global__ void __launch_bounds__(NTHR, 2) mega_fwd(Args args) {
amdhsa.kernels:
  - .agpr_count:     0
    .args:
      - .offset:         0
        .size:           192
        .value_kind:     by_value
      - .offset:         192
        .size:           4
        .value_kind:     hidden_block_count_x
      - .offset:         196
        .size:           4
        .value_kind:     hidden_block_count_y
      - .offset:         200
        .size:           4
        .value_kind:     hidden_block_count_z
      - .offset:         204
        .size:           2
        .value_kind:     hidden_group_size_x
      - .offset:         206
        .size:           2
        .value_kind:     hidden_group_size_y
      - .offset:         208
        .size:           2
        .value_kind:     hidden_group_size_z
      - .offset:         210
        .size:           2
        .value_kind:     hidden_remainder_x
      - .offset:         212
        .size:           2
        .value_kind:     hidden_remainder_y
      - .offset:         214
        .size:           2
        .value_kind:     hidden_remainder_z
      - .offset:         232
        .size:           8
        .value_kind:     hidden_global_offset_x
      - .offset:         240
        .size:           8
        .value_kind:     hidden_global_offset_y
      - .offset:         248
        .size:           8
        .value_kind:     hidden_global_offset_z
      - .offset:         256
        .size:           2
        .value_kind:     hidden_grid_dims
      - .offset:         280
        .size:           8
        .value_kind:     hidden_multigrid_sync_arg
      - .offset:         312
        .size:           4
        .value_kind:     hidden_dynamic_lds_size
    .group_segment_fixed_size: 0
    .kernarg_segment_align: 8
    .kernarg_segment_size: 448
    .language:       OpenCL C
    .language_version:
      - 2
      - 0
    .max_flat_workgroup_size: 512
    .name:           _Z8mega_fwd4Args
    .private_segment_fixed_size: 0
    .sgpr_count:     108
    .sgpr_spill_count: 277
    .symbol:         _Z8mega_fwd4Args.kd
    .uniform_work_group_size: 1
    .uses_dynamic_stack: false
    .vgpr_count:     255
    .vgpr_spill_count: 0
    .wavefront_size: 64
